# P8 epilogue main stores: v_mad_u32_u24 row offsets + saddr s[16:17] instead of v_mad_i64_i32 + 64-bit adds
# speedup vs baseline: 1.0047x; 1.0047x over previous
.LBB0_783:
	s_or_b64 exec, exec, s[64:65]
	s_waitcnt vmcnt(4)
	v_pk_mul_f32 v[160:161], v[160:161], s[34:35] op_sel_hi:[1,0]
	v_pk_mul_f32 v[158:159], v[158:159], s[34:35] op_sel_hi:[1,0]
	v_pk_mul_f32 v[148:149], v[148:149], s[34:35] op_sel_hi:[1,0]
	v_pk_mul_f32 v[146:147], v[146:147], s[34:35] op_sel_hi:[1,0]
	v_pk_mul_f32 v[156:157], v[156:157], s[34:35] op_sel_hi:[1,0]
	v_pk_mul_f32 v[154:155], v[154:155], s[34:35] op_sel_hi:[1,0]
	v_pk_fma_f32 v[162:163], v[160:161], v[204:205], v[148:149]
	v_pk_fma_f32 v[164:165], v[158:159], v[202:203], v[146:147]
	v_pk_mul_f32 v[152:153], v[152:153], s[34:35] op_sel_hi:[1,0]
	v_pk_mul_f32 v[150:151], v[150:151], s[34:35] op_sel_hi:[1,0]
	v_pk_fma_f32 v[164:165], v[154:155], v[198:199], v[164:165]
	v_pk_fma_f32 v[162:163], v[156:157], v[200:201], v[162:163]
	v_pk_fma_f32 v[166:167], v[160:161], v[200:201], v[148:149]
	v_pk_fma_f32 v[170:171], v[158:159], v[198:199], v[146:147]
	v_pk_fma_f32 v[162:163], v[128:129], v[152:153], v[162:163]
	v_pk_fma_f32 v[164:165], v[126:127], v[150:151], v[164:165]
	v_pk_fma_f32 v[170:171], v[126:127], v[154:155], v[170:171]
	v_pk_fma_f32 v[166:167], v[128:129], v[156:157], v[166:167]
	v_pk_fma_f32 v[128:129], v[128:129], v[160:161], v[148:149]
	v_pk_fma_f32 v[126:127], v[126:127], v[158:159], v[146:147]
	v_pk_fma_f32 v[166:167], v[124:125], v[152:153], v[166:167]
	v_pk_fma_f32 v[170:171], v[122:123], v[150:151], v[170:171]
	v_pk_fma_f32 v[126:127], v[122:123], v[154:155], v[126:127]
	v_pk_fma_f32 v[128:129], v[124:125], v[156:157], v[128:129]
	v_pk_fma_f32 v[124:125], v[124:125], v[160:161], v[148:149]
	v_pk_fma_f32 v[122:123], v[122:123], v[158:159], v[146:147]
	v_pk_fma_f32 v[128:129], v[120:121], v[152:153], v[128:129]
	v_pk_fma_f32 v[126:127], v[118:119], v[150:151], v[126:127]
	v_pk_fma_f32 v[118:119], v[118:119], v[154:155], v[122:123]
	v_pk_fma_f32 v[120:121], v[120:121], v[156:157], v[124:125]
	v_exp_f32_e64 v122, -v164
	v_exp_f32_e64 v124, -v162
	v_exp_f32_e64 v125, -v163
	v_exp_f32_e64 v123, -v165
	v_pk_fma_f32 v[120:121], v[116:117], v[152:153], v[120:121]
	v_pk_fma_f32 v[118:119], v[114:115], v[150:151], v[118:119]
	v_pk_fma_f32 v[114:115], v[124:125], s[34:35], s[34:35] op_sel_hi:[1,0,0]
	v_pk_fma_f32 v[116:117], v[122:123], s[34:35], s[34:35] op_sel_hi:[1,0,0]
	v_rcp_f32_e32 v114, v114
	v_rcp_f32_e32 v116, v116
	v_rcp_f32_e32 v117, v117
	v_rcp_f32_e32 v115, v115
	v_exp_f32_e64 v122, -v170
	v_exp_f32_e64 v124, -v166
	v_exp_f32_e64 v125, -v167
	v_exp_f32_e64 v123, -v171
	v_pk_mul_f32 v[110:111], v[110:111], v[164:165]
	v_pk_mul_f32 v[112:113], v[112:113], v[162:163]
	v_pk_mul_f32 v[116:117], v[110:111], v[116:117]
	v_pk_mul_f32 v[114:115], v[112:113], v[114:115]
	v_pk_fma_f32 v[110:111], v[124:125], s[34:35], s[34:35] op_sel_hi:[1,0,0]
	v_pk_fma_f32 v[112:113], v[122:123], s[34:35], s[34:35] op_sel_hi:[1,0,0]
	v_rcp_f32_e32 v110, v110
	v_rcp_f32_e32 v112, v112
	v_rcp_f32_e32 v113, v113
	v_rcp_f32_e32 v111, v111
	v_exp_f32_e64 v122, -v126
	v_exp_f32_e64 v124, -v128
	v_exp_f32_e64 v125, -v129
	v_exp_f32_e64 v123, -v127
	v_pk_mul_f32 v[106:107], v[106:107], v[170:171]
	v_pk_mul_f32 v[108:109], v[108:109], v[166:167]
	v_pk_mul_f32 v[164:165], v[106:107], v[112:113]
	v_pk_mul_f32 v[162:163], v[108:109], v[110:111]
	v_pk_fma_f32 v[106:107], v[124:125], s[34:35], s[34:35] op_sel_hi:[1,0,0]
	v_pk_fma_f32 v[108:109], v[122:123], s[34:35], s[34:35] op_sel_hi:[1,0,0]
	v_rcp_f32_e32 v106, v106
	v_rcp_f32_e32 v108, v108
	v_rcp_f32_e32 v109, v109
	v_rcp_f32_e32 v107, v107
	v_exp_f32_e64 v110, -v118
	v_exp_f32_e64 v112, -v120
	v_exp_f32_e64 v113, -v121
	v_exp_f32_e64 v111, -v119
	v_pk_mul_f32 v[102:103], v[102:103], v[126:127]
	v_pk_mul_f32 v[104:105], v[104:105], v[128:129]
	v_pk_mul_f32 v[124:125], v[102:103], v[108:109]
	v_pk_mul_f32 v[122:123], v[104:105], v[106:107]
	v_pk_fma_f32 v[102:103], v[112:113], s[34:35], s[34:35] op_sel_hi:[1,0,0]
	v_pk_fma_f32 v[104:105], v[110:111], s[34:35], s[34:35] op_sel_hi:[1,0,0]
	v_rcp_f32_e32 v102, v102
	v_rcp_f32_e32 v104, v104
	v_rcp_f32_e32 v103, v103
	v_rcp_f32_e32 v105, v105
	v_pk_mul_f32 v[98:99], v[98:99], v[118:119]
	v_pk_mul_f32 v[100:101], v[100:101], v[120:121]
	v_pk_mul_f32 v[112:113], v[132:133], s[34:35] op_sel_hi:[1,0]
	v_pk_mul_f32 v[118:119], v[100:101], v[102:103]
	v_pk_mul_f32 v[120:121], v[98:99], v[104:105]
	v_pk_mul_f32 v[100:101], v[144:145], s[34:35] op_sel_hi:[1,0]
	v_pk_mul_f32 v[98:99], v[142:143], s[34:35] op_sel_hi:[1,0]
	v_pk_mul_f32 v[110:111], v[130:131], s[34:35] op_sel_hi:[1,0]
	v_pk_mul_f32 v[104:105], v[140:141], s[34:35] op_sel_hi:[1,0]
	v_pk_mul_f32 v[102:103], v[138:139], s[34:35] op_sel_hi:[1,0]
	v_pk_fma_f32 v[126:127], v[100:101], v[196:197], v[112:113]
	v_pk_fma_f32 v[128:129], v[98:99], v[194:195], v[110:111]
	v_pk_mul_f32 v[108:109], v[136:137], s[34:35] op_sel_hi:[1,0]
	v_pk_mul_f32 v[106:107], v[134:135], s[34:35] op_sel_hi:[1,0]
	v_pk_fma_f32 v[128:129], v[102:103], v[190:191], v[128:129]
	v_pk_fma_f32 v[126:127], v[104:105], v[192:193], v[126:127]
	v_pk_fma_f32 v[130:131], v[100:101], v[192:193], v[112:113]
	v_pk_fma_f32 v[132:133], v[98:99], v[190:191], v[110:111]
	v_pk_fma_f32 v[126:127], v[96:97], v[108:109], v[126:127]
	v_pk_fma_f32 v[128:129], v[94:95], v[106:107], v[128:129]
	v_pk_fma_f32 v[132:133], v[94:95], v[102:103], v[132:133]
	v_pk_fma_f32 v[130:131], v[96:97], v[104:105], v[130:131]
	v_pk_fma_f32 v[96:97], v[96:97], v[100:101], v[112:113]
	v_pk_fma_f32 v[94:95], v[94:95], v[98:99], v[110:111]
	v_pk_fma_f32 v[130:131], v[92:93], v[108:109], v[130:131]
	v_pk_fma_f32 v[132:133], v[90:91], v[106:107], v[132:133]
	v_pk_fma_f32 v[96:97], v[92:93], v[104:105], v[96:97]
	v_pk_fma_f32 v[94:95], v[90:91], v[102:103], v[94:95]
	v_pk_fma_f32 v[92:93], v[92:93], v[100:101], v[112:113]
	v_pk_fma_f32 v[90:91], v[90:91], v[98:99], v[110:111]
	v_pk_fma_f32 v[96:97], v[88:89], v[108:109], v[96:97]
	v_pk_fma_f32 v[94:95], v[86:87], v[106:107], v[94:95]
	v_pk_fma_f32 v[88:89], v[88:89], v[104:105], v[92:93]
	v_pk_fma_f32 v[86:87], v[86:87], v[102:103], v[90:91]
	v_exp_f32_e64 v90, -v128
	v_exp_f32_e64 v92, -v126
	v_exp_f32_e64 v93, -v127
	v_exp_f32_e64 v91, -v129
	v_pk_fma_f32 v[84:85], v[84:85], v[108:109], v[88:89]
	v_pk_fma_f32 v[82:83], v[82:83], v[106:107], v[86:87]
	v_pk_fma_f32 v[86:87], v[92:93], s[34:35], s[34:35] op_sel_hi:[1,0,0]
	v_pk_fma_f32 v[88:89], v[90:91], s[34:35], s[34:35] op_sel_hi:[1,0,0]
	v_rcp_f32_e32 v86, v86
	v_rcp_f32_e32 v88, v88
	v_rcp_f32_e32 v89, v89
	v_rcp_f32_e32 v87, v87
	v_exp_f32_e64 v90, -v132
	v_exp_f32_e64 v92, -v130
	v_exp_f32_e64 v93, -v131
	v_exp_f32_e64 v91, -v133
	v_pk_mul_f32 v[78:79], v[78:79], v[128:129]
	v_pk_mul_f32 v[80:81], v[80:81], v[126:127]
	v_pk_mul_f32 v[78:79], v[78:79], v[88:89]
	v_pk_mul_f32 v[80:81], v[80:81], v[86:87]
	v_pk_fma_f32 v[86:87], v[92:93], s[34:35], s[34:35] op_sel_hi:[1,0,0]
	v_pk_fma_f32 v[88:89], v[90:91], s[34:35], s[34:35] op_sel_hi:[1,0,0]
	v_rcp_f32_e32 v86, v86
	v_rcp_f32_e32 v88, v88
	v_rcp_f32_e32 v89, v89
	v_rcp_f32_e32 v87, v87
	v_exp_f32_e64 v90, -v94
	v_exp_f32_e64 v92, -v96
	v_exp_f32_e64 v93, -v97
	v_exp_f32_e64 v91, -v95
	v_pk_mul_f32 v[74:75], v[74:75], v[132:133]
	v_pk_mul_f32 v[76:77], v[76:77], v[130:131]
	v_pk_mul_f32 v[74:75], v[74:75], v[88:89]
	v_pk_mul_f32 v[76:77], v[76:77], v[86:87]
	v_pk_fma_f32 v[86:87], v[92:93], s[34:35], s[34:35] op_sel_hi:[1,0,0]
	v_pk_fma_f32 v[88:89], v[90:91], s[34:35], s[34:35] op_sel_hi:[1,0,0]
	v_rcp_f32_e32 v86, v86
	v_rcp_f32_e32 v88, v88
	v_rcp_f32_e32 v89, v89
	v_rcp_f32_e32 v87, v87
	v_exp_f32_e64 v90, -v82
	v_exp_f32_e64 v91, -v83
	v_exp_f32_e64 v92, -v84
	v_exp_f32_e64 v93, -v85
	v_pk_mul_f32 v[72:73], v[72:73], v[96:97]
	v_pk_mul_f32 v[70:71], v[70:71], v[94:95]
	v_pk_mul_f32 v[72:73], v[72:73], v[86:87]
	v_pk_mul_f32 v[86:87], v[70:71], v[88:89]
	v_pk_fma_f32 v[88:89], v[90:91], s[34:35], s[34:35] op_sel_hi:[1,0,0]
	v_pk_fma_f32 v[70:71], v[92:93], s[34:35], s[34:35] op_sel_hi:[1,0,0]
	v_rcp_f32_e32 v88, v88
	v_rcp_f32_e32 v89, v89
	v_rcp_f32_e32 v70, v70
	v_rcp_f32_e32 v71, v71
	v_pk_mul_f32 v[66:67], v[66:67], v[82:83]
	v_pk_mul_f32 v[68:69], v[68:69], v[84:85]
	v_pk_mul_f32 v[84:85], v[66:67], v[88:89]
	v_or_b32_e32 v88, s49, v219
	v_cvt_pk_bf16_f32 v66, v78, v79
	v_mov_b64_e32 v[78:79], s[16:17]
	s_movk_i32 s51, 0x2c00
	v_pk_mul_f32 v[82:83], v[68:69], v[70:71]
	v_cvt_pk_bf16_f32 v67, v80, v81
	v_lshlrev_b64 v[70:71], 1, v[188:189]
	v_cvt_pk_bf16_f32 v68, v116, v117
	v_cvt_pk_bf16_f32 v69, v114, v115
	v_mad_u32_u24 v80, v88, s51, v70
	global_store_dwordx4 v80, v[66:69], s[16:17]
	v_cmp_lt_i32_e32 vcc, 14, v218
	s_mov_b64 s[62:63], 0
	v_cvt_pk_bf16_f32 v66, v74, v75
	v_or_b32_e32 v74, 1, v88
	v_cvt_pk_bf16_f32 v67, v76, v77
	v_cvt_pk_bf16_f32 v68, v164, v165
	v_cvt_pk_bf16_f32 v69, v162, v163
	v_mad_u32_u24 v74, v74, s51, v70
	global_store_dwordx4 v74, v[66:69], s[16:17]
	v_mov_b32_e32 v74, v1
	v_mov_b32_e32 v75, v1
	v_cvt_pk_bf16_f32 v67, v72, v73
	v_or_b32_e32 v72, 2, v88
	v_cvt_pk_bf16_f32 v66, v86, v87
	v_cvt_pk_bf16_f32 v68, v124, v125
	v_cvt_pk_bf16_f32 v69, v122, v123
	v_mad_u32_u24 v72, v72, s51, v70
	global_store_dwordx4 v72, v[66:69], s[16:17]
	v_or_b32_e32 v72, 3, v88
	v_cvt_pk_bf16_f32 v66, v84, v85
	v_cvt_pk_bf16_f32 v67, v82, v83
	v_cvt_pk_bf16_f32 v68, v120, v121
	v_cvt_pk_bf16_f32 v69, v118, v119
	v_mad_u32_u24 v72, v72, s51, v70
	global_store_dwordx4 v72, v[66:69], s[16:17]
	v_mov_b32_e32 v72, v1
	v_mov_b32_e32 v73, v1
	v_mov_b32_e32 v76, v1
	v_mov_b32_e32 v78, v1
	v_mov_b32_e32 v77, v1
	v_mov_b32_e32 v79, v1
	v_mov_b32_dpp v72, v30 row_shr:1 row_mask:0xf bank_mask:0xf
	v_mov_b32_dpp v74, v26 row_shr:1 row_mask:0xf bank_mask:0xf
	v_mov_b32_dpp v73, v31 row_shr:1 row_mask:0xf bank_mask:0xf
	v_mov_b32_dpp v75, v27 row_shr:1 row_mask:0xf bank_mask:0xf
	v_mov_b32_dpp v76, v32 row_shr:1 row_mask:0xf bank_mask:0xf
	v_mov_b32_dpp v78, v28 row_shr:1 row_mask:0xf bank_mask:0xf
	v_mov_b32_dpp v77, v33 row_shr:1 row_mask:0xf bank_mask:0xf
	v_mov_b32_dpp v79, v29 row_shr:1 row_mask:0xf bank_mask:0xf
	s_and_saveexec_b64 s[30:31], vcc
	s_xor_b64 s[64:65], exec, s[30:31]
	s_mov_b64 s[62:63], exec
	v_cvt_pk_bf16_f32 v66, v26, v27
	v_cvt_pk_bf16_f32 v67, v28, v29
	v_cvt_pk_bf16_f32 v68, v30, v31
	v_cvt_pk_bf16_f32 v69, v32, v33
	s_or_saveexec_b64 s[64:65], s[64:65]
	s_addk_i32 s49, 0x80
	s_ashr_i32 s30, s49, 6
	v_mad_i64_i32 v[80:81], s[72:73], s30, v235, v[184:185]
	v_lshlrev_b64 v[80:81], 4, v[80:81]
	v_mov_b64_e32 v[82:83], 0x72c00000
	s_xor_b64 exec, exec, s[64:65]
	s_cbranch_execz .LBB0_789
	v_cmp_eq_u32_e32 vcc, 0, v218
	s_mov_b64 s[74:75], s[62:63]
	s_and_saveexec_b64 s[72:73], vcc
	s_cbranch_execz .LBB0_788
	v_cvt_pk_bf16_f32 v82, v10, v11
	v_cvt_pk_bf16_f32 v83, v12, v13
	v_cvt_pk_bf16_f32 v84, v18, v19
	v_cvt_pk_bf16_f32 v85, v20, v21
	v_cvt_pk_bf16_f32 v66, v2, v3
	v_cvt_pk_bf16_f32 v67, v4, v5
	v_cvt_pk_bf16_f32 v68, v6, v7
	v_cvt_pk_bf16_f32 v69, v8, v9
	v_lshl_add_u64 v[86:87], s[40:41], 0, v[80:81]
	s_or_b64 s[74:75], s[62:63], exec
	global_store_dwordx4 v[86:87], v[82:85], off

.LBB0_799:
	s_or_b64 exec, exec, s[64:65]
	s_nop 0
	v_pk_fma_f32 v[66:67], v[52:53], v[160:161], v[148:149]
	v_pk_fma_f32 v[68:69], v[50:51], v[158:159], v[146:147]
	v_pk_fma_f32 v[66:67], v[60:61], v[156:157], v[66:67]
	v_pk_fma_f32 v[68:69], v[58:59], v[154:155], v[68:69]
	v_pk_fma_f32 v[64:65], v[64:65], v[152:153], v[66:67]
	v_pk_fma_f32 v[62:63], v[62:63], v[150:151], v[68:69]
	v_exp_f32_e64 v68, -v64
	v_exp_f32_e64 v66, -v62
	v_exp_f32_e64 v69, -v65
	v_exp_f32_e64 v67, -v63
	v_pk_mul_f32 v[56:57], v[56:57], v[64:65]
	v_pk_mul_f32 v[62:63], v[54:55], v[62:63]
	v_pk_fma_f32 v[54:55], v[68:69], s[34:35], s[34:35] op_sel_hi:[1,0,0]
	v_pk_fma_f32 v[64:65], v[66:67], s[34:35], s[34:35] op_sel_hi:[1,0,0]
	v_pk_fma_f32 v[66:67], v[44:45], v[160:161], v[148:149]
	v_pk_fma_f32 v[68:69], v[42:43], v[158:159], v[146:147]
	v_pk_fma_f32 v[66:67], v[52:53], v[156:157], v[66:67]
	v_pk_fma_f32 v[68:69], v[50:51], v[154:155], v[68:69]
	v_pk_fma_f32 v[60:61], v[60:61], v[152:153], v[66:67]
	v_pk_fma_f32 v[58:59], v[58:59], v[150:151], v[68:69]
	v_rcp_f32_e32 v64, v64
	v_rcp_f32_e32 v65, v65
	v_rcp_f32_e32 v54, v54
	v_rcp_f32_e32 v55, v55
	v_exp_f32_e64 v66, -v58
	v_exp_f32_e64 v68, -v60
	v_exp_f32_e64 v69, -v61
	v_exp_f32_e64 v67, -v59
	v_pk_mul_f32 v[54:55], v[56:57], v[54:55]
	v_pk_mul_f32 v[56:57], v[62:63], v[64:65]
	v_pk_fma_f32 v[62:63], v[68:69], s[34:35], s[34:35] op_sel_hi:[1,0,0]
	v_pk_fma_f32 v[64:65], v[66:67], s[34:35], s[34:35] op_sel_hi:[1,0,0]
	v_rcp_f32_e32 v62, v62
	v_rcp_f32_e32 v64, v64
	v_rcp_f32_e32 v63, v63
	v_rcp_f32_e32 v65, v65
	v_pk_mul_f32 v[48:49], v[48:49], v[60:61]
	v_pk_mul_f32 v[58:59], v[46:47], v[58:59]
	v_pk_fma_f32 v[60:61], v[158:159], v[80:81], v[146:147]
	v_pk_mul_f32 v[46:47], v[48:49], v[62:63]
	v_pk_mul_f32 v[48:49], v[58:59], v[64:65]
	v_pk_fma_f32 v[58:59], v[160:161], v[84:85], v[148:149]
	v_pk_fma_f32 v[60:61], v[42:43], v[154:155], v[60:61]
	v_pk_fma_f32 v[58:59], v[44:45], v[156:157], v[58:59]
	v_pk_fma_f32 v[50:51], v[50:51], v[150:151], v[60:61]
	v_pk_fma_f32 v[52:53], v[52:53], v[152:153], v[58:59]
	v_exp_f32_e64 v58, -v50
	v_exp_f32_e64 v59, -v51
	v_exp_f32_e64 v60, -v52
	v_exp_f32_e64 v61, -v53
	v_pk_mul_f32 v[40:41], v[40:41], v[52:53]
	v_pk_fma_f32 v[52:53], v[58:59], s[34:35], s[34:35] op_sel_hi:[1,0,0]
	v_pk_fma_f32 v[58:59], v[160:161], v[86:87], v[148:149]
	v_pk_mul_f32 v[38:39], v[38:39], v[50:51]
	v_pk_fma_f32 v[50:51], v[60:61], s[34:35], s[34:35] op_sel_hi:[1,0,0]
	v_pk_fma_f32 v[60:61], v[158:159], v[82:83], v[146:147]
	v_pk_fma_f32 v[58:59], v[156:157], v[84:85], v[58:59]
	v_pk_fma_f32 v[60:61], v[154:155], v[80:81], v[60:61]
	v_pk_fma_f32 v[44:45], v[44:45], v[152:153], v[58:59]
	v_pk_fma_f32 v[42:43], v[42:43], v[150:151], v[60:61]
	v_exp_f32_e64 v60, -v44
	v_exp_f32_e64 v61, -v45
	v_pk_mul_f32 v[36:37], v[36:37], v[44:45]
	v_pk_fma_f32 v[44:45], v[18:19], v[98:99], v[110:111]
	v_exp_f32_e64 v58, -v42
	v_exp_f32_e64 v59, -v43
	v_pk_mul_f32 v[34:35], v[34:35], v[42:43]
	v_pk_fma_f32 v[42:43], v[20:21], v[100:101], v[112:113]
	v_pk_fma_f32 v[44:45], v[26:27], v[102:103], v[44:45]
	v_pk_fma_f32 v[42:43], v[28:29], v[104:105], v[42:43]
	v_pk_fma_f32 v[30:31], v[30:31], v[106:107], v[44:45]
	v_pk_fma_f32 v[32:33], v[32:33], v[108:109], v[42:43]
	v_exp_f32_e64 v42, -v30
	v_exp_f32_e64 v43, -v31
	v_exp_f32_e64 v44, -v32
	v_exp_f32_e64 v45, -v33
	v_pk_mul_f32 v[24:25], v[24:25], v[32:33]
	v_pk_fma_f32 v[32:33], v[42:43], s[34:35], s[34:35] op_sel_hi:[1,0,0]
	v_pk_fma_f32 v[42:43], v[12:13], v[100:101], v[112:113]
	v_pk_mul_f32 v[22:23], v[22:23], v[30:31]
	v_pk_fma_f32 v[30:31], v[44:45], s[34:35], s[34:35] op_sel_hi:[1,0,0]
	v_pk_fma_f32 v[44:45], v[10:11], v[98:99], v[110:111]
	v_pk_fma_f32 v[42:43], v[20:21], v[104:105], v[42:43]
	v_pk_fma_f32 v[44:45], v[18:19], v[102:103], v[44:45]
	v_pk_fma_f32 v[28:29], v[28:29], v[108:109], v[42:43]
	v_pk_fma_f32 v[26:27], v[26:27], v[106:107], v[44:45]
	v_exp_f32_e64 v44, -v28
	v_exp_f32_e64 v45, -v29
	v_pk_mul_f32 v[16:17], v[16:17], v[28:29]
	v_pk_fma_f32 v[28:29], v[98:99], v[72:73], v[110:111]
	v_exp_f32_e64 v42, -v26
	v_exp_f32_e64 v43, -v27
	v_pk_mul_f32 v[14:15], v[14:15], v[26:27]
	v_pk_fma_f32 v[26:27], v[100:101], v[76:77], v[112:113]
	v_pk_fma_f32 v[28:29], v[10:11], v[102:103], v[28:29]
	v_pk_fma_f32 v[26:27], v[12:13], v[104:105], v[26:27]
	v_pk_fma_f32 v[18:19], v[18:19], v[106:107], v[28:29]
	v_pk_fma_f32 v[20:21], v[20:21], v[108:109], v[26:27]
	v_exp_f32_e64 v26, -v18
	v_exp_f32_e64 v27, -v19
	v_exp_f32_e64 v28, -v20
	v_exp_f32_e64 v29, -v21
	v_pk_mul_f32 v[8:9], v[8:9], v[20:21]
	v_pk_fma_f32 v[20:21], v[26:27], s[34:35], s[34:35] op_sel_hi:[1,0,0]
	v_pk_fma_f32 v[26:27], v[100:101], v[78:79], v[112:113]
	v_pk_mul_f32 v[6:7], v[6:7], v[18:19]
	v_pk_fma_f32 v[18:19], v[28:29], s[34:35], s[34:35] op_sel_hi:[1,0,0]
	v_pk_fma_f32 v[28:29], v[98:99], v[74:75], v[110:111]
	v_pk_fma_f32 v[26:27], v[104:105], v[76:77], v[26:27]
	v_pk_fma_f32 v[28:29], v[102:103], v[72:73], v[28:29]
	v_pk_fma_f32 v[12:13], v[12:13], v[108:109], v[26:27]
	v_rcp_f32_e32 v18, v18
	v_rcp_f32_e32 v19, v19
	v_pk_fma_f32 v[10:11], v[10:11], v[106:107], v[28:29]
	v_exp_f32_e64 v28, -v12
	v_exp_f32_e64 v29, -v13
	v_rcp_f32_e32 v52, v52
	v_rcp_f32_e32 v53, v53
	v_rcp_f32_e32 v50, v50
	v_rcp_f32_e32 v51, v51
	v_rcp_f32_e32 v20, v20
	v_rcp_f32_e32 v21, v21
	v_exp_f32_e64 v26, -v10
	v_exp_f32_e64 v27, -v11
	v_pk_mul_f32 v[8:9], v[8:9], v[18:19]
	v_pk_fma_f32 v[18:19], v[28:29], s[34:35], s[34:35] op_sel_hi:[1,0,0]
	v_pk_mul_f32 v[40:41], v[40:41], v[50:51]
	v_pk_mul_f32 v[38:39], v[38:39], v[52:53]
	v_pk_fma_f32 v[50:51], v[60:61], s[34:35], s[34:35] op_sel_hi:[1,0,0]
	v_pk_fma_f32 v[52:53], v[58:59], s[34:35], s[34:35] op_sel_hi:[1,0,0]
	v_pk_mul_f32 v[6:7], v[6:7], v[20:21]
	v_pk_fma_f32 v[20:21], v[26:27], s[34:35], s[34:35] op_sel_hi:[1,0,0]
	v_rcp_f32_e32 v18, v18
	v_rcp_f32_e32 v19, v19
	v_rcp_f32_e32 v52, v52
	v_rcp_f32_e32 v50, v50
	v_rcp_f32_e32 v51, v51
	v_rcp_f32_e32 v53, v53
	v_rcp_f32_e32 v20, v20
	v_rcp_f32_e32 v21, v21
	v_rcp_f32_e32 v32, v32
	v_rcp_f32_e32 v33, v33
	v_rcp_f32_e32 v30, v30
	v_rcp_f32_e32 v31, v31
	v_pk_mul_f32 v[4:5], v[4:5], v[12:13]
	v_pk_mul_f32 v[2:3], v[2:3], v[10:11]
	v_pk_mul_f32 v[4:5], v[4:5], v[18:19]
	v_or_b32_e32 v18, s49, v219
	v_mov_b64_e32 v[10:11], s[16:17]
	s_movk_i32 s49, 0x2c00
	v_pk_mul_f32 v[36:37], v[36:37], v[50:51]
	v_pk_mul_f32 v[34:35], v[34:35], v[52:53]
	v_pk_mul_f32 v[2:3], v[2:3], v[20:21]
	v_pk_mul_f32 v[24:25], v[24:25], v[30:31]
	v_pk_mul_f32 v[22:23], v[22:23], v[32:33]
	v_pk_fma_f32 v[30:31], v[44:45], s[34:35], s[34:35] op_sel_hi:[1,0,0]
	v_pk_fma_f32 v[32:33], v[42:43], s[34:35], s[34:35] op_sel_hi:[1,0,0]
	v_cvt_pk_bf16_f32 v2, v2, v3
	v_cvt_pk_bf16_f32 v3, v4, v5
	v_cvt_pk_bf16_f32 v4, v34, v35
	v_cvt_pk_bf16_f32 v5, v36, v37
	v_mad_u32_u24 v12, v18, s49, v70
	v_rcp_f32_e32 v32, v32
	v_rcp_f32_e32 v30, v30
	v_rcp_f32_e32 v31, v31
	v_rcp_f32_e32 v33, v33
	global_store_dwordx4 v12, v[2:5], s[16:17]
	s_andn2_b64 vcc, exec, s[38:39]
	v_pk_mul_f32 v[16:17], v[16:17], v[30:31]
	v_cvt_pk_bf16_f32 v2, v6, v7
	v_or_b32_e32 v6, 1, v18
	v_cvt_pk_bf16_f32 v3, v8, v9
	v_cvt_pk_bf16_f32 v4, v38, v39
	v_cvt_pk_bf16_f32 v5, v40, v41
	v_mad_u32_u24 v6, v6, s49, v70
	global_store_dwordx4 v6, v[2:5], s[16:17]
	v_or_b32_e32 v6, 2, v18
	v_pk_mul_f32 v[14:15], v[14:15], v[32:33]
	v_cvt_pk_bf16_f32 v2, v14, v15
	v_cvt_pk_bf16_f32 v3, v16, v17
	v_cvt_pk_bf16_f32 v4, v48, v49
	v_cvt_pk_bf16_f32 v5, v46, v47
	v_mad_u32_u24 v6, v6, s49, v70
	global_store_dwordx4 v6, v[2:5], s[16:17]
	v_or_b32_e32 v6, 3, v18
	v_cvt_pk_bf16_f32 v2, v22, v23
	v_cvt_pk_bf16_f32 v3, v24, v25
	v_cvt_pk_bf16_f32 v4, v56, v57
	v_cvt_pk_bf16_f32 v5, v54, v55
	v_mad_u32_u24 v6, v6, s49, v70
	s_mov_b64 s[38:39], -1
	global_store_dwordx4 v6, v[2:5], s[16:17]
	s_cbranch_vccnz .LBB0_760
	s_andn2_b64 vcc, exec, s[14:15]
	s_cbranch_vccnz .LBB0_759
	s_barrier
	s_branch .LBB0_759
